# combination plus SEL 4-tile barrier interval (static LDS 31744) on top of the previous combination
# baseline (speedup 1.0000x reference)
; DI float bflo(unsigned w) { return __uint_as_float(w << 16); }
; DI float bfhi(unsigned w) { return __uint_as_float(w & 0xffff0000u); }
; #define GATES WSP(float, WS_GATES)
; #define MASKS WSP(unsigned, WS_MASK)
; #define lds fresh_lds(lds0)
; template <int DQK, int MODE> ...
;     ...
;     FL_GLOAD(t0);
;     __syncthreads();
;     FL_LSTORE(0);
;     if (t0 + 1 < t1) FL_GLOAD(t0 + 1);
;     __syncthreads();
; __global__ void __launch_bounds__(512) mega_fwd(Params P) {
;     ...
;                 const int qb = 31 - it / 24, r24 = it % 24, bh = r24 % 12, b = bh / 6, h = bh % 6, g = h / 3, q0 = qb * 256;
;                 const size_t rb = (size_t)b * SEQ; const size_t qrow = rb + q0 + 32 * wid + r32;
;                 if (r24 < 12) {
;                     f32x16 tot[2]; tot[0] = (f32x16){}; tot[1] = (f32x16){};
;                     flash_unit<96, MODE_CAUSAL>(lds, wv0, QMLA + (rb + q0) * 576 + h * 96, 576, KVB + rb * 768 + h * 64, 768, PROJ + rb * NPROJ + PC_KR, NPROJ,
;                                                 KVB + rb * 768 + 384 + h * 64, 768, q0, 0, (q0 + 256) / 64, 0.10206207261596577f * LOG2E, (u32x4){}, 1.f, tot, nullptr, WSP(float, WS_ROPE));
;                     store_o(tot, HN + qrow * DM + h * 64, hi);
;                 } else {
;                     const float g1 = GATES[qrow * 32 + h * 3 + 1], g2 = GATES[qrow * 32 + h * 3 + 2];
;                     const u32x4 mw = *(const u32x4*)(MASKS + ((size_t)(b * 2 + g) * SEQ + q0 + 32 * wid + r32) * 4);
;                     f32x16 tot[2];
;                     { const bf16_t* oc = OCMP + qrow * 384 + h * 64;
; #pragma unroll
;                       for (int d0 = 0; d0 < 2; ++d0)
; #pragma unroll
;                           for (int j = 0; j < 4; ++j) { const u32x2 w = *(const u32x2*)(oc + 32 * d0 + 8 * j + 4 * hi); tot[d0][4 * j] = bflo(w.x); tot[d0][4 * j + 1] = bfhi(w.x); tot[d0][4 * j + 2] = bflo(w.y); tot[d0][4 * j + 3] = bfhi(w.y); } }
;                     const bf16_t* Qp = PROJ + (rb + q0) * NPROJ + PC_NQ + 64 * h;
;                     flash_unit<64, MODE_SEL>(lds, wv0, Qp, NPROJ, PROJ + rb * NPROJ + PC_KS + 64 * g, NPROJ, nullptr, 0, PROJ + rb * NPROJ + PC_VS + 64 * g, NPROJ,
;                                              q0, 0, (q0 + 256) / 64, 0.125f * LOG2E, mw, g1, tot, nullptr);
.La3_item:
	s_cmpk_lt_i32 s34, 0x300
	s_cbranch_scc0 .LBB0_1372
	s_mul_hi_i32 s0, s34, 0xd5555555
	s_lshr_b32 s1, s0, 31
	s_lshr_b32 s0, s0, 2
	s_add_i32 s4, s0, s1
	s_mul_hi_i32 s0, s34, 0x2aaaaaab
	s_lshr_b32 s1, s0, 31
	s_lshr_b32 s0, s0, 2
	s_add_i32 s0, s0, s1
	s_mul_i32 s0, s0, 24
	s_sub_i32 s6, s34, s0
	s_mul_i32 s0, s6, 43
	s_sext_i32_i16 s1, s0
	s_lshr_b32 s1, s1, 9
	s_bfe_u32 s0, s0, 0x1000f
	s_add_i32 s0, s1, s0
	s_mul_i32 s0, s0, 12
	s_sub_i32 s1, s6, s0
	s_bfe_i32 s0, s1, 0x80000
	s_mul_i32 s0, s0, 43
	s_bfe_u32 s5, s0, 0x1000f
	s_bfe_u32 s0, s0, 0x80008
	s_add_i32 s0, s0, s5
	s_mul_i32 s5, s0, 6
	s_sub_i32 s1, s1, s5
	s_lshl_b32 s35, s4, 8
	s_bfe_i64 s[8:9], s[0:1], 0x80000
	s_add_i32 s36, s35, 0x1f00
	s_lshl_b64 s[4:5], s[8:9], 13
	s_add_u32 s26, s4, s36
	s_addc_u32 s27, s5, 0
	s_sext_i32_i8 s37, s1
	v_lshl_add_u64 v[180:181], s[26:27], 0, v[174:175]
	s_mov_b64 s[4:5], -1
	s_cmp_gt_i32 s6, 11
	s_mul_hi_i32 s45, s8, 0x2800000
	s_mul_i32 s46, s8, 0x2800000
	s_cbranch_scc0 .LBB0_1346
	s_bfe_i32 s1, s1, 0x80000
	s_mulk_i32 s1, 0x56
	s_bfe_u32 s4, s1, 0x1000f
	s_bfe_u32 s1, s1, 0x80008
	s_add_i32 s1, s1, s4
	s_sext_i32_i8 s6, s1
	s_sext_i32_i8 s0, s0
	s_lshl_b32 s0, s0, 14
	s_lshl_b32 s1, s6, 13
	s_add_i32 s1, s1, s0
	s_add_u32 s0, s1, s36
	s_addc_u32 s1, 0, 0
	v_mov_b64_e32 v[6:7], s[18:19]
	v_lshl_add_u64 v[4:5], s[0:1], 0, v[174:175]
	v_mad_u64_u32 v[6:7], s[0:1], v180, s72, v[6:7]
	v_mov_b32_e32 v0, v7
	v_lshlrev_b64 v[2:3], 7, v[180:181]
	v_mad_u64_u32 v[8:9], s[0:1], v181, s72, v[0:1]
	s_mul_i32 s80, s37, 3
	v_lshl_add_u64 v[2:3], s[14:15], 0, v[2:3]
	s_mul_i32 s0, s27, 0x1400
	s_mul_hi_u32 s1, s26, 0x1400
	v_lshl_add_u64 v[2:3], s[80:81], 2, v[2:3]
	s_lshl_b32 s9, s37, 6
	s_lshl_b32 s80, s37, 7
	s_add_i32 s1, s1, s0
	s_mul_i32 s0, s26, 0x1400
	s_add_u32 s0, s39, s0
	v_mov_b32_e32 v7, v8
	s_addc_u32 s1, s40, s1
	v_lshl_add_u64 v[6:7], v[6:7], 0, s[80:81]
	v_mov_b32_e32 v179, v1
	s_add_u32 s30, s0, s80
	v_lshl_add_u64 v[4:5], v[4:5], 4, s[16:17]
	v_lshl_add_u64 v[6:7], v[6:7], 0, v[178:179]
	s_addc_u32 s31, s1, 0
	s_mov_b32 s1, s81
	v_mov_b32_e32 v0, v1
	flat_load_dwordx2 v[182:183], v[2:3] offset:4
	s_nop 0
	flat_load_dwordx4 v[2:5], v[4:5]
	s_nop 0
	flat_load_dwordx2 v[198:199], v[6:7]
	flat_load_dwordx2 v[196:197], v[6:7] offset:16
	flat_load_dwordx2 v[194:195], v[6:7] offset:32
	flat_load_dwordx2 v[192:193], v[6:7] offset:48
	flat_load_dwordx2 v[190:191], v[6:7] offset:64
	flat_load_dwordx2 v[188:189], v[6:7] offset:80
	flat_load_dwordx2 v[186:187], v[6:7] offset:96
	flat_load_dwordx2 v[184:185], v[6:7] offset:112
	v_readlane_b32 s7, v254, 6
	v_mbcnt_lo_u32_b32 v0, -1, v0
	v_mbcnt_hi_u32_b32 v26, -1, v0
	v_and_b32_e32 v27, 31, v26
	v_bfe_u32 v28, v26, 5, 1
	v_or_b32_e32 v0, s7, v27
	v_mov_b64_e32 v[6:7], s[30:31]
	v_mad_i64_i32 v[6:7], s[4:5], v0, s69, v[6:7]
	v_lshlrev_b32_e32 v0, 4, v28
	v_lshl_add_u64 v[6:7], v[6:7], 0, v[0:1]
	s_waitcnt vmcnt(0)
	flat_load_dwordx4 v[84:87], v[6:7] offset:832
	flat_load_dwordx4 v[80:83], v[6:7] offset:864
	flat_load_dwordx4 v[10:13], v[6:7] offset:896
	s_nop 0
	flat_load_dwordx4 v[6:9], v[6:7] offset:928
	s_add_u32 s0, s39, s46
	v_or_b32_e32 v14, s79, v26
	s_addc_u32 s4, s40, s45
	s_lshl_b32 s5, s6, 7
	v_and_b32_e32 v15, 7, v26
	v_ashrrev_i32_e32 v24, 3, v14
	s_add_u32 s28, s0, s5
	v_lshlrev_b32_e32 v29, 4, v15
	v_mul_lo_u32 v14, v24, s69
	v_mov_b32_e32 v23, v1
	s_addc_u32 s29, s4, 0
	v_or_b32_e32 v22, v29, v14
	v_lshl_add_u64 v[18:19], s[28:29], 0, v[22:23]
	s_movk_i32 s4, 0x90
	v_mul_lo_u32 v23, v24, s4
	v_mov_b32_e32 v25, v1
	v_add3_u32 v129, s1, v23, v29
	v_add_u32_e32 v24, 0x50000, v22
	v_lshl_add_u64 v[24:25], s[28:29], 0, v[24:25]
	v_add_u32_e32 v226, 0xa0000, v22
	v_mov_b32_e32 v227, v1
	v_lshl_add_u64 v[226:227], s[28:29], 0, v[226:227]
	v_add_u32_e32 v232, 0xf0000, v22
	v_mov_b32_e32 v233, v1
	v_lshl_add_u64 v[232:233], s[28:29], 0, v[232:233]
	v_mad_u32_u24 v131, v27, s4, v0
	v_lshlrev_b32_e32 v128, 2, v28
	v_lshrrev_b32_e32 v0, 2, v26
	s_add_i32 s0, s35, 0x2000
	s_add_i32 s48, s36, s7
	v_and_or_b32 v0, v0, 3, v128
	v_mov_b32_e32 v30, v1
	v_mov_b32_e32 v31, v1
	s_lshr_b32 s47, s0, 6
	v_mov_b32_e32 v23, v1
	v_mov_b32_e32 v28, v1
	v_mov_b32_e32 v29, v1
	s_mov_b32 s53, s81
	s_mov_b32 s50, 0
	s_or_b32 s49, s48, 31
	s_add_i32 s0, s47, -1
	v_mov_b32_e32 v179, 0
	s_mov_b32 s51, 63
	global_load_dwordx4 v[14:17], v[18:19], off offset:2112
	s_nop 0
	global_load_dwordx4 v[18:21], v[18:19], off offset:2368
	global_load_dwordx4 v[88:91], v[24:25], off offset:2368
	global_load_dwordx4 v[92:95], v[24:25], off offset:2112
	global_load_dwordx4 v[222:225], v[226:227], off offset:2368
	global_load_dwordx4 v[218:221], v[226:227], off offset:2112
	global_load_dwordx4 v[238:241], v[232:233], off offset:2368
	global_load_dwordx4 v[234:237], v[232:233], off offset:2112
	s_waitcnt vmcnt(0) lgkmcnt(0)
	s_waitcnt lgkmcnt(0)
	s_barrier
	s_waitcnt vmcnt(0)
	v_add_u32_e32 v230, 0x12000, v129
	ds_write_b128 v129, v[14:17]
	ds_write_b128 v230, v[18:21]
	v_add_u32_e32 v229, 0x2400, v129
	v_add_u32_e32 v230, 0x2400, v230
	ds_write_b128 v229, v[92:95]
	ds_write_b128 v230, v[88:91]
	v_add_u32_e32 v229, 0x2400, v229
	v_add_u32_e32 v230, 0x2400, v230
	ds_write_b128 v229, v[218:221]
	ds_write_b128 v230, v[222:225]
	v_add_u32_e32 v229, 0x2400, v229
	v_add_u32_e32 v230, 0x2400, v230
	ds_write_b128 v229, v[234:237]
	ds_write_b128 v230, v[238:241]
	s_cmp_lt_u32 s47, 5
	s_cbranch_scc1 .Lselq_pro_done
	v_add_u32_e32 v228, 0x140000, v22
	v_mov_b32_e32 v229, v1
	v_lshl_add_u64 v[228:229], s[28:29], 0, v[228:229]
	global_load_dwordx4 v[92:95], v[228:229], off offset:2112
	global_load_dwordx4 v[88:91], v[228:229], off offset:2368
	v_add_u32_e32 v230, 0x190000, v22
	v_mov_b32_e32 v231, v1
	v_lshl_add_u64 v[230:231], s[28:29], 0, v[230:231]
	global_load_dwordx4 v[218:221], v[230:231], off offset:2112
	global_load_dwordx4 v[222:225], v[230:231], off offset:2368
